# mixer-B loop: K staged two tiles ahead and V one tile ahead so one workgroup barrier per key tile instead of two
# speedup vs baseline: 1.0115x; 1.0076x over previous
; #define LAS __attribute__((address_space(3)))
; __device__ __forceinline__ float half_max(float v) { auto rr = __builtin_amdgcn_permlane32_swap(__float_as_uint(v), __float_as_uint(v), false, false); return fmaxf(__uint_as_float(rr[0]), __uint_as_float(rr[1])); }
; #define SWAIT() asm volatile("s_waitcnt vmcnt(4)" ::: "memory")
; __device__ __forceinline__ void partialSM(f32x16& p0, f32x16& p1, const LAS float* tbp, int relc, float cL, float cR, float& m_reg, float& mn, float& alpha) {
;     float cb = 0.f;
;     if (relc + 63 <= -559) cb = cL;
;     else if (relc - 31 >= 559) cb = cR;
;     else {
; #pragma unroll
;         for (int r = 0; r < 16; ++r) { p0[r] += tbp[(r & 3) + 8 * (r >> 2)]; p1[r] += tbp[32 + (r & 3) + 8 * (r >> 2)]; }
;     }
;     float pmax = p0[0];
; #pragma unroll
;     for (int r = 1; r < 16; ++r) pmax = fmaxf(pmax, p0[r]);
; #pragma unroll
;     for (int r = 0; r < 16; ++r) pmax = fmaxf(pmax, p1[r]);
;     pmax = half_max(pmax) + cb;
;     if (__builtin_expect(__all(pmax - m_reg <= 8.f), 1)) { mn = m_reg; alpha = 1.f; }
;     else { mn = fmaxf(m_reg, pmax); alpha = __builtin_amdgcn_exp2f(m_reg - mn); m_reg = mn; }
;     const float sh = mn - cb;
; #pragma unroll
;     for (int r = 0; r < 16; ++r) { p0[r] -= sh; p1[r] -= sh; }
; #pragma unroll
;     for (int r = 0; r < 16; ++r) p0[r] = __builtin_amdgcn_exp2f(p0[r]);
; }
; __device__ __forceinline__ void finishSM(f32x16& p0, f32x16& p1, float alpha, float& l_reg, bf16x8& pa0, bf16x8& pa1, bf16x8& pa2, bf16x8& pa3) {
; #pragma unroll
;     for (int r = 0; r < 16; ++r) p1[r] = __builtin_amdgcn_exp2f(p1[r]);
; __device__ __forceinline__ void unit(LAS unsigned char* lds, const bf16* __restrict__ PROJ, bf16* __restrict__ MIXED, const float* __restrict__ subln_g, float lam, int R0, int seq, int h, int qb) {
;     ...
;     f32x16 pA0, pA1, pB0, pB1; float mnA, mnB, alA, alB; bf16x8 pa0, pa1, pa2, pa3; const int NT = seq / 64;
;     constexpr int SE = 0, SO = 1;
;     SLOAD(SE, 0); asm volatile("s_waitcnt vmcnt(0)" ::: "memory"); SWRITE(0, SE); __syncthreads();
;     qkt(pA0, pA1, K_lds, qr, r32, cb0); partialSM(pA0, pA1, tbq, rc0, cL, cR, m_reg, mnA, alA);
;     SLOAD(SO, 64); if (2 < NT) SLOAD(SE, 128);
;     SWAIT(); SWRITE(1, SO); __syncthreads();
;     for (int j = 1; j + 1 < NT; j += 2) {
.LBB0_259:
	v_add_co_u32_e32 v38, vcc, s54, v32
	s_nop 6
	v_max_f32_e32 v58, v1, v1
	v_addc_co_u32_e32 v39, vcc, 0, v33, vcc
	v_add_co_u32_e32 v42, vcc, s55, v32
	v_max_f32_e32 v59, v0, v0
	s_nop 0
	v_addc_co_u32_e32 v43, vcc, 0, v33, vcc
	v_add_co_u32_e32 v46, vcc, s54, v34
	global_load_dwordx4 v[38:41], v[38:39], off
	s_nop 0
	global_load_dwordx4 v[42:45], v[42:43], off
	v_addc_co_u32_e32 v47, vcc, 0, v35, vcc
	v_add_co_u32_e32 v50, vcc, s55, v34
	v_max_f32_e32 v58, v59, v58
	s_nop 0
	v_addc_co_u32_e32 v51, vcc, 0, v35, vcc
	v_add_co_u32_e32 v54, vcc, s56, v34
	global_load_dwordx4 v[46:49], v[46:47], off
	s_nop 0
	global_load_dwordx4 v[50:53], v[50:51], off
	v_addc_co_u32_e32 v55, vcc, 0, v35, vcc
	v_add_co_u32_e32 v34, vcc, s57, v34
	s_and_b32 s4, s33, 0x3fffffc0
	s_nop 0
	v_addc_co_u32_e32 v35, vcc, 0, v35, vcc
	v_add_co_u32_e32 v56, vcc, s56, v32
	s_lshl_b32 s4, s4, 2
	s_nop 0
	v_addc_co_u32_e32 v57, vcc, 0, v33, vcc
	v_add_co_u32_e32 v32, vcc, s57, v32
	s_add_i32 s4, s4, 0
	s_nop 0
	v_addc_co_u32_e32 v33, vcc, 0, v33, vcc
	global_load_dwordx4 v[116:119], v[54:55], off
	global_load_dwordx4 v[112:115], v[34:35], off
	global_load_dwordx4 v[124:127], v[56:57], off
	global_load_dwordx4 v[120:123], v[32:33], off
	v_max3_f32 v32, v58, v2, v3
	v_max3_f32 v32, v32, v4, v5
	v_max3_f32 v32, v32, v6, v7
	v_max3_f32 v32, v32, v8, v9
	v_max3_f32 v32, v32, v10, v11
	v_max3_f32 v32, v32, v12, v13
	v_max3_f32 v32, v32, v14, v15
	v_max3_f32 v32, v32, v16, v17
	v_max3_f32 v32, v32, v18, v19
	v_max3_f32 v32, v32, v20, v21
	v_max3_f32 v32, v32, v22, v23
	v_max3_f32 v32, v32, v24, v25
	v_max3_f32 v32, v32, v26, v27
	v_max3_f32 v32, v32, v28, v29
	v_max3_f32 v32, v32, v30, v31
	v_mov_b32_e32 v33, v32
	s_nop 1
	v_permlane32_swap_b32_e32 v32, v33
	v_max_f32_e32 v33, v33, v33
	v_max_f32_e32 v32, v32, v32
	v_max_f32_e32 v32, v32, v33
	v_add_f32_e32 v32, v37, v32
	v_add_f32_e32 v33, 0x7149f2ca, v32
	s_lshr_b32 s90, s96, 6
	s_add_i32 s4, s4, 0x18000
	v_cmp_ge_f32_e32 vcc, s35, v33
	s_cmp_eq_u64 vcc, exec
	v_max_f32_e32 v32, 0xf149f2ca, v32
	s_cselect_b64 vcc, -1, 0
	v_cndmask_b32_e32 v148, v32, v214, vcc
	v_sub_f32_e32 v33, v148, v37
	v_sub_f32_e32 v0, v0, v33
	v_exp_f32_e32 v145, v0
	v_sub_f32_e32 v0, v1, v33
	v_exp_f32_e32 v158, v0
	v_sub_f32_e32 v0, v2, v33
	v_exp_f32_e32 v146, v0
	v_sub_f32_e32 v0, v3, v33
	v_exp_f32_e32 v159, v0
	v_sub_f32_e32 v0, v4, v33
	v_exp_f32_e32 v147, v0
	v_sub_f32_e32 v0, v5, v33
	v_exp_f32_e32 v228, v0
	v_sub_f32_e32 v0, v6, v33
	v_exp_f32_e32 v157, v0
	v_sub_f32_e32 v0, v7, v33
	v_exp_f32_e32 v231, v0
	v_sub_f32_e32 v0, v8, v33
	v_exp_f32_e32 v149, v0
	v_sub_f32_e32 v0, v9, v33
	v_exp_f32_e32 v153, v0
	v_sub_f32_e32 v0, v10, v33
	v_exp_f32_e32 v150, v0
	v_sub_f32_e32 v0, v11, v33
	v_exp_f32_e32 v154, v0
	v_sub_f32_e32 v0, v12, v33
	v_sub_f32_e32 v140, v16, v33
	v_sub_f32_e32 v16, 0xf149f2ca, v32
	v_exp_f32_e32 v151, v0
	v_sub_f32_e32 v0, v13, v33
	v_exp_f32_e32 v16, v16
	v_exp_f32_e32 v155, v0
	v_sub_f32_e32 v0, v14, v33
	v_exp_f32_e32 v152, v0
	v_sub_f32_e32 v0, v15, v33
	v_exp_f32_e32 v156, v0
	v_lshl_add_u32 v215, v169, 2, s4
	v_lshl_add_u32 v179, v171, 2, s4
	s_lshl_b64 s[4:5], s[6:7], 8
	s_waitcnt vmcnt(4)
	s_add_u32 s4, s29, s4
	v_lshlrev_b32_e32 v0, 2, v36
	v_mov_b32_e32 v14, v161
	v_mov_b32_e32 v15, v161
	s_waitcnt vmcnt(7)
	ds_write_b128 v210, v[38:41] offset:16384
	s_waitcnt vmcnt(6)
	ds_write_b128 v211, v[42:45] offset:16384
	s_waitcnt vmcnt(5)
	ds_write_b128 v212, v[46:49] offset:49152
	s_waitcnt vmcnt(4)
	ds_write_b128 v213, v[50:53] offset:49152
	v_sub_f32_e32 v141, v17, v33
	v_sub_f32_e32 v142, v18, v33
	v_sub_f32_e32 v143, v19, v33
	v_sub_f32_e32 v130, v20, v33
	v_sub_f32_e32 v131, v21, v33
	v_sub_f32_e32 v132, v22, v33
	v_sub_f32_e32 v133, v23, v33
	v_sub_f32_e32 v134, v24, v33
	v_sub_f32_e32 v135, v25, v33
	v_sub_f32_e32 v138, v26, v33
	v_sub_f32_e32 v139, v27, v33
	v_sub_f32_e32 v128, v28, v33
	v_sub_f32_e32 v129, v29, v33
	v_sub_f32_e32 v136, v30, v33
	v_sub_f32_e32 v137, v31, v33
	v_cndmask_b32_e64 v224, v16, 1.0, vcc
	s_addc_u32 s5, s28, s5
	v_sub_u32_e32 v223, v188, v0
	v_mov_b32_e32 v0, v161
	v_mov_b32_e32 v1, v161
	v_mov_b32_e32 v2, v161
	v_mov_b32_e32 v3, v161
	v_mov_b32_e32 v4, v161
	v_mov_b32_e32 v5, v161
	v_mov_b32_e32 v6, v161
	v_mov_b32_e32 v7, v161
	v_mov_b32_e32 v8, v161
	v_mov_b32_e32 v9, v161
	v_mov_b32_e32 v10, v161
	v_mov_b32_e32 v11, v161
	v_mov_b32_e32 v12, v161
	v_mov_b32_e32 v13, v161
	v_mov_b64_e32 v[62:63], v[14:15]
	v_mov_b64_e32 v[46:47], v[14:15]
	v_mov_b64_e32 v[30:31], v[14:15]
	s_mov_b32 s33, 2
	v_lshl_add_u64 v[182:183], v[166:167], 0, s[4:5]
	s_sub_i32 s6, 64, s97
	v_mov_b32_e32 v216, 0
	v_mov_b64_e32 v[60:61], v[12:13]
	v_mov_b64_e32 v[58:59], v[10:11]
	v_mov_b64_e32 v[56:57], v[8:9]
	v_mov_b64_e32 v[54:55], v[6:7]
	v_mov_b64_e32 v[52:53], v[4:5]
	v_mov_b64_e32 v[50:51], v[2:3]
	v_mov_b64_e32 v[48:49], v[0:1]
	v_mov_b64_e32 v[44:45], v[12:13]
	v_mov_b64_e32 v[42:43], v[10:11]
	v_mov_b64_e32 v[40:41], v[8:9]
	v_mov_b64_e32 v[38:39], v[6:7]
	v_mov_b64_e32 v[36:37], v[4:5]
	v_mov_b64_e32 v[34:35], v[2:3]
	v_mov_b64_e32 v[32:33], v[0:1]
	v_mov_b64_e32 v[28:29], v[12:13]
	v_mov_b64_e32 v[26:27], v[10:11]
	v_mov_b64_e32 v[24:25], v[8:9]
	v_mov_b64_e32 v[22:23], v[6:7]
	v_mov_b64_e32 v[20:21], v[4:5]
	v_mov_b64_e32 v[18:19], v[2:3]
	v_mov_b64_e32 v[16:17], v[0:1]
	s_waitcnt lgkmcnt(0)
	s_barrier
	v_mov_b32_e32 v250, v148
	v_mov_b32_e32 v251, 1.0
	v_mov_b32_e32 v232, v145
	v_mov_b32_e32 v233, v158
	v_mov_b32_e32 v234, v146
	v_mov_b32_e32 v235, v159
	v_mov_b32_e32 v236, v147
	v_mov_b32_e32 v237, v228
	v_mov_b32_e32 v238, v157
	v_mov_b32_e32 v239, v231
	v_mov_b32_e32 v240, v149
	v_mov_b32_e32 v241, v153
	v_mov_b32_e32 v242, v150
	v_mov_b32_e32 v243, v154
	v_mov_b32_e32 v244, v151
	v_mov_b32_e32 v245, v155
	v_mov_b32_e32 v246, v152
	v_mov_b32_e32 v247, v156
	v_exp_f32_e32 v144, v140
	v_exp_f32_e32 v145, v141
	v_exp_f32_e32 v146, v142
	v_exp_f32_e32 v147, v143
	v_exp_f32_e32 v148, v130
	v_exp_f32_e32 v149, v131
	v_exp_f32_e32 v150, v132
	v_exp_f32_e32 v151, v133
	v_exp_f32_e32 v152, v134
	v_exp_f32_e32 v153, v135
	v_exp_f32_e32 v154, v138
	v_exp_f32_e32 v155, v139
	v_exp_f32_e32 v156, v128
	v_exp_f32_e32 v157, v129
	v_exp_f32_e32 v158, v136
	v_exp_f32_e32 v159, v137
	s_waitcnt vmcnt(2)
	ds_write_b128 v212, v[112:115] offset:32768
	ds_write_b128 v213, v[116:119] offset:32768
	s_waitcnt lgkmcnt(0)
	s_mov_b32 s4, 0xffee0000
	s_mov_b32 s5, -1
	v_lshl_add_u64 v[112:113], v[182:183], 0, s[4:5]
	global_load_dwordx4 v[112:115], v[112:113], off offset:-2048
	s_mov_b32 s4, 0xfff40000
	v_lshl_add_u64 v[116:117], v[182:183], 0, s[4:5]
	global_load_dwordx4 v[116:119], v[116:117], off offset:-2048
.Lmb_loop:
	s_add_i32 s33, s33, 2
	s_cmp_ge_u32 s33, s90
	s_cselect_b64 s[26:27], -1, 0
	s_mov_b32 s28, 0
	v_mov_b32_e32 v249, v181
	s_cmpk_lt_i32 s6, 0xfd93
	s_cbranch_scc1 .Lmb_cls_h1
	v_mov_b32_e32 v249, v217
	s_cmpk_gt_i32 s6, 0x24d
	s_cbranch_scc1 .Lmb_cls_h1
	s_mov_b32 s28, 1
	v_mov_b32_e32 v249, 0

; #define SBAR() __builtin_amdgcn_sched_barrier(0)
; #define SLOAD(i, k0) do { sr_[i].vs0 = *(const bf16x8*)(Vh + (size_t)((k0) + sr) * PW + sc); sr_[i].vs1 = *(const bf16x8*)(Vh + (size_t)((k0) + 32 + sr) * PW + sc); \
;     sr_[i].ks0 = *(const bf16x8*)(Kh + (size_t)((k0) + sr) * PW + sc); sr_[i].ks1 = *(const bf16x8*)(Kh + (size_t)((k0) + 32 + sr) * PW + sc); } while (0)
; #define SWRITE(b, i) do { *(LAS bf16x8*)(V_lds + (b) * SHM_V + vst0) = sr_[i].vs0; *(LAS bf16x8*)(V_lds + (b) * SHM_V + vst1) = sr_[i].vs1; const int kc = sc * 2; \
;     *(LAS bf16x8*)(K_lds + (b) * SHM_K + KSWZ(sr, kc)) = sr_[i].ks0; *(LAS bf16x8*)(K_lds + (b) * SHM_K + KSWZ(32 + sr, kc)) = sr_[i].ks1; } while (0)
; #define SWAIT() asm volatile("s_waitcnt vmcnt(4)" ::: "memory")
; #define RESC(a) do { if (__any((a) < 1.f)) { if (hi == 0) al_l[r32] = (a); LDS_WAIT(); \
;     _Pragma("unroll") for (int r = 0; r < 16; ++r) { const float av = al_l[crow(r, hi)]; _Pragma("unroll") for (int d = 0; d < 4; ++d) o[d][r] *= av; } } } while (0)
; __device__ __forceinline__ void unit(LAS unsigned char* lds, const bf16* __restrict__ PROJ, bf16* __restrict__ MIXED, const float* __restrict__ subln_g, float lam, int R0, int seq, int h, int qb) {
;     ...
;         SLOAD(SO, (j + 2) * 64); SBAR();
;         pv_d0(o, vb0, pa0, pa1, pa2, pa3); partialSM(pB0, pB1, tbq + j * 64, rc0 + j * 64, cL, cR, m_reg, mnB, alB);
;         __syncthreads(); SWAIT(); SWRITE(0, SE);
;         RESC(alB); __syncthreads();
;         SBAR(); qkt(pA0, pA1, K_lds, qr, r32, cb0);
;         finishSM(pB0, pB1, alB, l_reg, pa0, pa1, pa2, pa3); SBAR();
;         if (j + 3 < NT) SLOAD(SE, (j + 3) * 64); SBAR();
.Lmb_qkj_h1:
	s_mov_b32 s4, 0xffee0000
	s_mov_b32 s5, -1
	v_lshl_add_u64 v[128:129], v[182:183], 0, s[4:5]
	global_load_dwordx4 v[128:131], v[128:129], off
	s_mov_b32 s4, 0xfff40000
	v_lshl_add_u64 v[140:141], v[182:183], 0, s[4:5]
	global_load_dwordx4 v[140:143], v[140:141], off
	s_and_b64 vcc, exec, s[26:27]
	s_cbranch_vccnz .Lmb_skipk1
	s_mov_b32 s4, 0xfffa0000
	v_lshl_add_u64 v[132:133], v[182:183], 0, s[4:5]
	global_load_dwordx4 v[132:135], v[132:133], off offset:-2048
	global_load_dwordx4 v[136:139], v[182:183], off offset:-2048

; #define LAS __attribute__((address_space(3)))
; __device__ __forceinline__ void partialSM(f32x16& p0, f32x16& p1, const LAS float* tbp, int relc, float cL, float cR, float& m_reg, float& mn, float& alpha) {
;     float cb = 0.f;
;     if (relc + 63 <= -559) cb = cL;
;     else if (relc - 31 >= 559) cb = cR;
;     else {
; #pragma unroll
;         for (int r = 0; r < 16; ++r) { p0[r] += tbp[(r & 3) + 8 * (r >> 2)]; p1[r] += tbp[32 + (r & 3) + 8 * (r >> 2)]; }
;     }
;     float pmax = p0[0];
; #pragma unroll
;     for (int r = 1; r < 16; ++r) pmax = fmaxf(pmax, p0[r]);
; #pragma unroll
;     for (int r = 0; r < 16; ++r) pmax = fmaxf(pmax, p1[r]);
;     pmax = half_max(pmax) + cb;
;     if (__builtin_expect(__all(pmax - m_reg <= 8.f), 1)) { mn = m_reg; alpha = 1.f; }
;     else { mn = fmaxf(m_reg, pmax); alpha = __builtin_amdgcn_exp2f(m_reg - mn); m_reg = mn; }
;     const float sh = mn - cb;
; #pragma unroll
;     for (int r = 0; r < 16; ++r) { p0[r] -= sh; p1[r] -= sh; }
; #pragma unroll
;     for (int r = 0; r < 16; ++r) p0[r] = __builtin_amdgcn_exp2f(p0[r]);
; }
; template <int D0> __device__ __forceinline__ void pv_one(f32x16& od, int vb, bf16x8 pa0, bf16x8 pa1, bf16x8 pa2, bf16x8 pa3) {
;     s16x4 l0 = tr_read<v_rd_off(D0, 0, 0)>(vb), h0 = tr_read<v_rd_off(D0, 0, 1)>(vb), l1 = tr_read<v_rd_off(D0, 1, 0)>(vb), h1 = tr_read<v_rd_off(D0, 1, 1)>(vb);
;     s16x4 l2 = tr_read<v_rd_off(D0, 2, 0)>(vb), h2 = tr_read<v_rd_off(D0, 2, 1)>(vb), l3 = tr_read<v_rd_off(D0, 3, 0)>(vb), h3 = tr_read<v_rd_off(D0, 3, 1)>(vb);
;     asm volatile("s_waitcnt lgkmcnt(0)" : "+v"(l0), "+v"(h0), "+v"(l1), "+v"(h1), "+v"(l2), "+v"(h2), "+v"(l3), "+v"(h3) :: "memory");
;     od = __builtin_amdgcn_mfma_f32_32x32x16_bf16(pa0, PKV(l0, h0), od, 0, 0, 0);
;     od = __builtin_amdgcn_mfma_f32_32x32x16_bf16(pa1, PKV(l1, h1), od, 0, 0, 0);
;     od = __builtin_amdgcn_mfma_f32_32x32x16_bf16(pa2, PKV(l2, h2), od, 0, 0, 0);
;     od = __builtin_amdgcn_mfma_f32_32x32x16_bf16(pa3, PKV(l3, h3), od, 0, 0, 0);
; }
; __device__ __forceinline__ void pv_d0(f32x16* o, int vb, bf16x8 pa0, bf16x8 pa1, bf16x8 pa2, bf16x8 pa3) {
;     pv_one<0>(o[0], vb, pa0, pa1, pa2, pa3); pv_one<1>(o[1], vb, pa0, pa1, pa2, pa3); pv_one<2>(o[2], vb, pa0, pa1, pa2, pa3); pv_one<3>(o[3], vb, pa0, pa1, pa2, pa3);
; }
.Lmb_pv_h1:
	s_waitcnt lgkmcnt(0)
	v_mfma_f32_32x32x16_bf16 v[0:15], v[232:235], v[240:243], v[0:15]
	ds_read_b64_tr_b16 v[240:241], v175 offset:512
	ds_read_b64_tr_b16 v[242:243], v175 offset:2560
	v_max3_f32 v254, v80, v81, v82
	v_max3_f32 v255, v83, v84, v85
	v_max3_f32 v254, v254, v86, v87
	v_max3_f32 v255, v255, v88, v89
	v_max3_f32 v254, v254, v90, v91
	v_max3_f32 v255, v255, v92, v93
	v_mfma_f32_32x32x16_bf16 v[0:15], v[236:239], v[244:247], v[0:15]
	ds_read_b64_tr_b16 v[244:245], v175 offset:4608
	ds_read_b64_tr_b16 v[246:247], v175 offset:6656
	v_max3_f32 v254, v254, v94, v95
	v_max3_f32 v255, v255, v64, v65
	v_max3_f32 v254, v254, v66, v67
	v_max3_f32 v255, v255, v68, v69
	v_max3_f32 v254, v254, v70, v71
	v_max3_f32 v255, v255, v72, v73
	v_mfma_f32_32x32x16_bf16 v[0:15], v[144:147], v[152:155], v[0:15]
	ds_read_b64_tr_b16 v[152:153], v175 offset:8704
	ds_read_b64_tr_b16 v[154:155], v175 offset:10752
	v_max3_f32 v254, v254, v74, v75
	v_max3_f32 v255, v255, v76, v77
	v_max3_f32 v254, v254, v78, v79
	v_max_f32_e32 v254, v254, v255
	v_mov_b32_e32 v255, v254
	v_mfma_f32_32x32x16_bf16 v[0:15], v[148:151], v[156:159], v[0:15]
	ds_read_b64_tr_b16 v[156:157], v175 offset:12800
	ds_read_b64_tr_b16 v[158:159], v175 offset:14848
	v_permlane32_swap_b32_e32 v254, v255
	v_max_f32_e32 v254, v254, v255
	v_add_f32_e32 v254, v249, v254
	v_sub_f32_e32 v255, v254, v250
	v_cmp_ge_f32_e32 vcc, s35, v255
	v_max_f32_e32 v255, v250, v254
	s_waitcnt lgkmcnt(0)
	v_mfma_f32_32x32x16_bf16 v[48:63], v[232:235], v[240:243], v[48:63]
	ds_read_b64_tr_b16 v[240:241], v175 offset:1024
	ds_read_b64_tr_b16 v[242:243], v175 offset:3072
	v_sub_f32_e32 v248, v250, v255
	v_exp_f32_e32 v248, v248
	v_sub_f32_e32 v252, v255, v249
	v_sub_f32_e32 v254, v250, v249
	s_cmp_eq_u64 vcc, exec
	s_cselect_b64 s[4:5], -1, 0
	v_cndmask_b32_e64 v251, v248, 1.0, s[4:5]
	v_mfma_f32_32x32x16_bf16 v[48:63], v[236:239], v[244:247], v[48:63]
	ds_read_b64_tr_b16 v[244:245], v175 offset:5120
	ds_read_b64_tr_b16 v[246:247], v175 offset:7168
	v_cndmask_b32_e64 v250, v255, v250, s[4:5]
	v_cndmask_b32_e64 v252, v252, v254, s[4:5]
	v_sub_f32_e32 v80, v80, v252
	v_sub_f32_e32 v81, v81, v252
	v_sub_f32_e32 v82, v82, v252
	v_sub_f32_e32 v83, v83, v252
	v_mfma_f32_32x32x16_bf16 v[48:63], v[144:147], v[152:155], v[48:63]
	ds_read_b64_tr_b16 v[152:153], v175 offset:9216
	ds_read_b64_tr_b16 v[154:155], v175 offset:11264
	v_sub_f32_e32 v84, v84, v252
	v_sub_f32_e32 v85, v85, v252
	v_sub_f32_e32 v86, v86, v252
	v_sub_f32_e32 v87, v87, v252
	v_sub_f32_e32 v88, v88, v252
	v_sub_f32_e32 v89, v89, v252
	v_mfma_f32_32x32x16_bf16 v[48:63], v[148:151], v[156:159], v[48:63]
	ds_read_b64_tr_b16 v[156:157], v175 offset:13312
	ds_read_b64_tr_b16 v[158:159], v175 offset:15360
	v_sub_f32_e32 v90, v90, v252
	v_sub_f32_e32 v91, v91, v252
	v_sub_f32_e32 v92, v92, v252
	v_sub_f32_e32 v93, v93, v252
	v_sub_f32_e32 v94, v94, v252
	v_sub_f32_e32 v95, v95, v252
	s_waitcnt lgkmcnt(0)
	v_mfma_f32_32x32x16_bf16 v[32:47], v[232:235], v[240:243], v[32:47]
	ds_read_b64_tr_b16 v[240:241], v175 offset:1536
	ds_read_b64_tr_b16 v[242:243], v175 offset:3584
	v_exp_f32_e32 v80, v80
	v_sub_f32_e32 v64, v64, v252
	v_exp_f32_e32 v81, v81
	v_sub_f32_e32 v65, v65, v252
	v_mfma_f32_32x32x16_bf16 v[32:47], v[236:239], v[244:247], v[32:47]
	ds_read_b64_tr_b16 v[244:245], v175 offset:5632
	ds_read_b64_tr_b16 v[246:247], v175 offset:7680
	v_exp_f32_e32 v82, v82
	v_sub_f32_e32 v66, v66, v252
	v_exp_f32_e32 v83, v83
	v_sub_f32_e32 v67, v67, v252
	v_mfma_f32_32x32x16_bf16 v[32:47], v[144:147], v[152:155], v[32:47]
	ds_read_b64_tr_b16 v[152:153], v175 offset:9728
	ds_read_b64_tr_b16 v[154:155], v175 offset:11776
	v_exp_f32_e32 v84, v84
	v_sub_f32_e32 v68, v68, v252
	v_exp_f32_e32 v85, v85
	v_sub_f32_e32 v69, v69, v252
	v_mfma_f32_32x32x16_bf16 v[32:47], v[148:151], v[156:159], v[32:47]
	ds_read_b64_tr_b16 v[156:157], v175 offset:13824
	ds_read_b64_tr_b16 v[158:159], v175 offset:15872
	v_exp_f32_e32 v86, v86
	v_sub_f32_e32 v70, v70, v252
	v_exp_f32_e32 v87, v87
	v_sub_f32_e32 v71, v71, v252
	s_waitcnt lgkmcnt(0)
	v_mfma_f32_32x32x16_bf16 v[16:31], v[232:235], v[240:243], v[16:31]
	v_exp_f32_e32 v88, v88
	v_sub_f32_e32 v72, v72, v252
	v_exp_f32_e32 v89, v89
	v_sub_f32_e32 v73, v73, v252
	v_mfma_f32_32x32x16_bf16 v[16:31], v[236:239], v[244:247], v[16:31]
	v_exp_f32_e32 v90, v90
	v_sub_f32_e32 v74, v74, v252
	v_exp_f32_e32 v91, v91
	v_sub_f32_e32 v75, v75, v252
	v_mfma_f32_32x32x16_bf16 v[16:31], v[144:147], v[152:155], v[16:31]
	v_exp_f32_e32 v92, v92
	v_sub_f32_e32 v76, v76, v252
	v_exp_f32_e32 v93, v93
	v_sub_f32_e32 v77, v77, v252
	v_mfma_f32_32x32x16_bf16 v[16:31], v[148:151], v[156:159], v[16:31]
	v_exp_f32_e32 v94, v94
	v_sub_f32_e32 v78, v78, v252
	v_exp_f32_e32 v95, v95
	v_sub_f32_e32 v79, v79, v252
	s_barrier
	s_waitcnt vmcnt(4)
	s_and_b64 vcc, exec, s[26:27]
	s_cbranch_vccz .Lmb_w1
	s_waitcnt vmcnt(2)
; #define SWRITE(b, i) do { *(LAS bf16x8*)(V_lds + (b) * SHM_V + vst0) = sr_[i].vs0; *(LAS bf16x8*)(V_lds + (b) * SHM_V + vst1) = sr_[i].vs1; const int kc = sc * 2; \
;     *(LAS bf16x8*)(K_lds + (b) * SHM_K + KSWZ(sr, kc)) = sr_[i].ks0; *(LAS bf16x8*)(K_lds + (b) * SHM_K + KSWZ(32 + sr, kc)) = sr_[i].ks1; } while (0)
; #define SWAIT() asm volatile("s_waitcnt vmcnt(4)" ::: "memory")
; #define RESC(a) do { if (__any((a) < 1.f)) { if (hi == 0) al_l[r32] = (a); LDS_WAIT(); \
;     _Pragma("unroll") for (int r = 0; r < 16; ++r) { const float av = al_l[crow(r, hi)]; _Pragma("unroll") for (int d = 0; d < 4; ++d) o[d][r] *= av; } } } while (0)
; __device__ __forceinline__ void unit(LAS unsigned char* lds, const bf16* __restrict__ PROJ, bf16* __restrict__ MIXED, const float* __restrict__ subln_g, float lam, int R0, int seq, int h, int qb) {
;     ...
;         __syncthreads(); SWAIT(); SWRITE(0, SE);
;         RESC(alB); __syncthreads();
.Lmb_w1:
	ds_write_b128 v210, v[120:123]
	ds_write_b128 v211, v[124:127]
	ds_write_b128 v212, v[112:115] offset:49152
	ds_write_b128 v213, v[116:119] offset:49152
	s_and_b64 vcc, exec, s[4:5]
	s_cbranch_vccnz .Lmb_nr_h1
	s_and_saveexec_b64 s[28:29], s[0:1]
	ds_write_b32 v215, v251 offset:128
	s_or_b64 exec, exec, s[28:29]
	s_waitcnt lgkmcnt(0)
	ds_read_b128 v[112:115], v179 offset:224
	ds_read_b128 v[116:119], v179 offset:192
	ds_read_b128 v[120:123], v179 offset:160
	ds_read_b128 v[124:127], v179 offset:128
	s_waitcnt lgkmcnt(0)
	s_nop 3
	v_pk_mul_f32 v[14:15], v[14:15], v[114:115]
	v_pk_mul_f32 v[12:13], v[12:13], v[112:113]
	v_pk_mul_f32 v[10:11], v[10:11], v[118:119]
	v_pk_mul_f32 v[8:9], v[8:9], v[116:117]
	v_pk_mul_f32 v[6:7], v[6:7], v[122:123]
	v_pk_mul_f32 v[4:5], v[4:5], v[120:121]
	v_pk_mul_f32 v[2:3], v[2:3], v[126:127]
	v_pk_mul_f32 v[0:1], v[0:1], v[124:125]
	v_pk_mul_f32 v[62:63], v[62:63], v[114:115]
	v_pk_mul_f32 v[60:61], v[60:61], v[112:113]
	v_pk_mul_f32 v[58:59], v[58:59], v[118:119]
	v_pk_mul_f32 v[56:57], v[56:57], v[116:117]
	v_pk_mul_f32 v[54:55], v[54:55], v[122:123]
	v_pk_mul_f32 v[52:53], v[52:53], v[120:121]
	v_pk_mul_f32 v[50:51], v[50:51], v[126:127]
	v_pk_mul_f32 v[48:49], v[48:49], v[124:125]
	v_pk_mul_f32 v[46:47], v[46:47], v[114:115]
	v_pk_mul_f32 v[44:45], v[44:45], v[112:113]
	v_pk_mul_f32 v[42:43], v[42:43], v[118:119]
	v_pk_mul_f32 v[40:41], v[40:41], v[116:117]
	v_pk_mul_f32 v[38:39], v[38:39], v[122:123]
	v_pk_mul_f32 v[36:37], v[36:37], v[120:121]
	v_pk_mul_f32 v[34:35], v[34:35], v[126:127]
	v_pk_mul_f32 v[32:33], v[32:33], v[124:125]
	v_pk_mul_f32 v[30:31], v[30:31], v[114:115]
	v_pk_mul_f32 v[28:29], v[28:29], v[112:113]
	v_pk_mul_f32 v[26:27], v[26:27], v[118:119]
	v_pk_mul_f32 v[24:25], v[24:25], v[116:117]
	v_pk_mul_f32 v[22:23], v[22:23], v[122:123]
	v_pk_mul_f32 v[20:21], v[20:21], v[120:121]
	v_pk_mul_f32 v[18:19], v[18:19], v[126:127]
	v_pk_mul_f32 v[16:17], v[16:17], v[124:125]
.Lmb_nr_h1:
	v_exp_f32_e32 v64, v64
	v_exp_f32_e32 v65, v65
	v_exp_f32_e32 v66, v66
	v_exp_f32_e32 v67, v67
	v_exp_f32_e32 v68, v68
	v_exp_f32_e32 v69, v69
	v_exp_f32_e32 v70, v70
	v_exp_f32_e32 v71, v71
	v_exp_f32_e32 v72, v72
	v_exp_f32_e32 v73, v73
	v_exp_f32_e32 v74, v74
	v_exp_f32_e32 v75, v75
	v_exp_f32_e32 v76, v76
	v_exp_f32_e32 v77, v77
	v_exp_f32_e32 v78, v78
	v_exp_f32_e32 v79, v79
	s_add_i32 s4, s6, 64
	s_mov_b32 s28, 0
	v_mov_b32_e32 v249, v181
	s_cmpk_lt_i32 s4, 0xfd93
	s_cbranch_scc1 .Lmb_cls_h2
	v_mov_b32_e32 v249, v217
	s_cmpk_gt_i32 s4, 0x24d
	s_cbranch_scc1 .Lmb_cls_h2
	s_mov_b32 s28, 1
	v_mov_b32_e32 v249, 0

; #define SBAR() __builtin_amdgcn_sched_barrier(0)
; #define SLOAD(i, k0) do { sr_[i].vs0 = *(const bf16x8*)(Vh + (size_t)((k0) + sr) * PW + sc); sr_[i].vs1 = *(const bf16x8*)(Vh + (size_t)((k0) + 32 + sr) * PW + sc); \
;     sr_[i].ks0 = *(const bf16x8*)(Kh + (size_t)((k0) + sr) * PW + sc); sr_[i].ks1 = *(const bf16x8*)(Kh + (size_t)((k0) + 32 + sr) * PW + sc); } while (0)
; __device__ __forceinline__ void unit(LAS unsigned char* lds, const bf16* __restrict__ PROJ, bf16* __restrict__ MIXED, const float* __restrict__ subln_g, float lam, int R0, int seq, int h, int qb) {
;     ...
;         if (j + 3 < NT) SLOAD(SE, (j + 3) * 64); SBAR();
.Lmb_qkj_h2:
	s_and_b64 vcc, exec, s[26:27]
	s_cbranch_vccnz .Lmb_skipld
	s_mov_b32 s4, 0xfffa0000
	s_mov_b32 s5, -1
	v_lshl_add_u64 v[120:121], v[182:183], 0, s[4:5]
	global_load_dwordx4 v[120:123], v[120:121], off
	global_load_dwordx4 v[124:127], v[182:183], off
	s_mov_b64 s[4:5], 0x60000
	v_lshl_add_u64 v[112:113], v[182:183], 0, s[4:5]
	global_load_dwordx4 v[112:115], v[112:113], off offset:-2048
	s_mov_b64 s[4:5], 0xc0000
	v_lshl_add_u64 v[116:117], v[182:183], 0, s[4:5]
	global_load_dwordx4 v[116:119], v[116:117], off offset:-2048

; #define SWRITE(b, i) do { *(LAS bf16x8*)(V_lds + (b) * SHM_V + vst0) = sr_[i].vs0; *(LAS bf16x8*)(V_lds + (b) * SHM_V + vst1) = sr_[i].vs1; const int kc = sc * 2; \
;     *(LAS bf16x8*)(K_lds + (b) * SHM_K + KSWZ(sr, kc)) = sr_[i].ks0; *(LAS bf16x8*)(K_lds + (b) * SHM_K + KSWZ(32 + sr, kc)) = sr_[i].ks1; } while (0)
; #define SWAIT() asm volatile("s_waitcnt vmcnt(4)" ::: "memory")
; #define RESC(a) do { if (__any((a) < 1.f)) { if (hi == 0) al_l[r32] = (a); LDS_WAIT(); \
;     _Pragma("unroll") for (int r = 0; r < 16; ++r) { const float av = al_l[crow(r, hi)]; _Pragma("unroll") for (int d = 0; d < 4; ++d) o[d][r] *= av; } } } while (0)
; __device__ __forceinline__ void unit(LAS unsigned char* lds, const bf16* __restrict__ PROJ, bf16* __restrict__ MIXED, const float* __restrict__ subln_g, float lam, int R0, int seq, int h, int qb) {
;     ...
;         __syncthreads(); SWAIT(); SWRITE(1, SO);
;         RESC(alA); __syncthreads();
;     }
.Lmb_w2:
	ds_write_b128 v210, v[128:131] offset:16384
	ds_write_b128 v211, v[140:143] offset:16384
	ds_write_b128 v212, v[132:135] offset:32768
	ds_write_b128 v213, v[136:139] offset:32768
	s_and_b64 vcc, exec, s[4:5]
	s_cbranch_vccnz .Lmb_nr_h2
	s_and_saveexec_b64 s[28:29], s[0:1]
	ds_write_b32 v215, v251 offset:128
	s_or_b64 exec, exec, s[28:29]
	s_waitcnt lgkmcnt(0)
	ds_read_b128 v[128:131], v179 offset:224
	ds_read_b128 v[132:135], v179 offset:192
	ds_read_b128 v[136:139], v179 offset:160
	ds_read_b128 v[140:143], v179 offset:128
	s_waitcnt lgkmcnt(0)
	s_nop 3
	v_pk_mul_f32 v[14:15], v[14:15], v[130:131]
	v_pk_mul_f32 v[12:13], v[12:13], v[128:129]
	v_pk_mul_f32 v[10:11], v[10:11], v[134:135]
	v_pk_mul_f32 v[8:9], v[8:9], v[132:133]
	v_pk_mul_f32 v[6:7], v[6:7], v[138:139]
	v_pk_mul_f32 v[4:5], v[4:5], v[136:137]
	v_pk_mul_f32 v[2:3], v[2:3], v[142:143]
	v_pk_mul_f32 v[0:1], v[0:1], v[140:141]
	v_pk_mul_f32 v[62:63], v[62:63], v[130:131]
	v_pk_mul_f32 v[60:61], v[60:61], v[128:129]
	v_pk_mul_f32 v[58:59], v[58:59], v[134:135]
	v_pk_mul_f32 v[56:57], v[56:57], v[132:133]
	v_pk_mul_f32 v[54:55], v[54:55], v[138:139]
	v_pk_mul_f32 v[52:53], v[52:53], v[136:137]
	v_pk_mul_f32 v[50:51], v[50:51], v[142:143]
	v_pk_mul_f32 v[48:49], v[48:49], v[140:141]
	v_pk_mul_f32 v[46:47], v[46:47], v[130:131]
	v_pk_mul_f32 v[44:45], v[44:45], v[128:129]
	v_pk_mul_f32 v[42:43], v[42:43], v[134:135]
	v_pk_mul_f32 v[40:41], v[40:41], v[132:133]
	v_pk_mul_f32 v[38:39], v[38:39], v[138:139]
	v_pk_mul_f32 v[36:37], v[36:37], v[136:137]
	v_pk_mul_f32 v[34:35], v[34:35], v[142:143]
	v_pk_mul_f32 v[32:33], v[32:33], v[140:141]
	v_pk_mul_f32 v[30:31], v[30:31], v[130:131]
	v_pk_mul_f32 v[28:29], v[28:29], v[128:129]
	v_pk_mul_f32 v[26:27], v[26:27], v[134:135]
	v_pk_mul_f32 v[24:25], v[24:25], v[132:133]
	v_pk_mul_f32 v[22:23], v[22:23], v[138:139]
	v_pk_mul_f32 v[20:21], v[20:21], v[136:137]
	v_pk_mul_f32 v[18:19], v[18:19], v[142:143]
	v_pk_mul_f32 v[16:17], v[16:17], v[140:141]
.Lmb_nr_h2:
	v_exp_f32_e32 v144, v144
	v_exp_f32_e32 v145, v145
	v_exp_f32_e32 v146, v146
	v_exp_f32_e32 v147, v147
	v_exp_f32_e32 v148, v148
	v_exp_f32_e32 v149, v149
	v_exp_f32_e32 v150, v150
	v_exp_f32_e32 v151, v151
	v_exp_f32_e32 v152, v152
	v_exp_f32_e32 v153, v153
	v_exp_f32_e32 v154, v154
	v_exp_f32_e32 v155, v155
	v_exp_f32_e32 v156, v156
	v_exp_f32_e32 v157, v157
	v_exp_f32_e32 v158, v158
	v_exp_f32_e32 v159, v159
	s_mov_b64 s[4:5], 0x180000
	v_lshl_add_u64 v[182:183], v[182:183], 0, s[4:5]
	s_addk_i32 s6, 0x80
	v_add_u32_e32 v223, 0x200, v223
	s_and_b64 vcc, exec, s[26:27]
	s_cbranch_vccz .Lmb_loop
	s_mov_b32 s28, 0
	v_mov_b32_e32 v249, v181
	s_cmpk_lt_i32 s6, 0xfd93
	s_cbranch_scc1 .Lmb_cls_pe
	v_mov_b32_e32 v249, v217
	s_cmpk_gt_i32 s6, 0x24d
	s_cbranch_scc1 .Lmb_cls_pe
	s_mov_b32 s28, 1
	v_mov_b32_e32 v249, 0

; #define LAS __attribute__((address_space(3)))
; #define SBAR() __builtin_amdgcn_sched_barrier(0)
; __device__ __forceinline__ float half_max(float v) { auto rr = __builtin_amdgcn_permlane32_swap(__float_as_uint(v), __float_as_uint(v), false, false); return fmaxf(__uint_as_float(rr[0]), __uint_as_float(rr[1])); }
; #define RESC(a) do { if (__any((a) < 1.f)) { if (hi == 0) al_l[r32] = (a); LDS_WAIT(); \
;     _Pragma("unroll") for (int r = 0; r < 16; ++r) { const float av = al_l[crow(r, hi)]; _Pragma("unroll") for (int d = 0; d < 4; ++d) o[d][r] *= av; } } } while (0)
; __device__ __forceinline__ void partialSM(f32x16& p0, f32x16& p1, const LAS float* tbp, int relc, float cL, float cR, float& m_reg, float& mn, float& alpha) {
;     float cb = 0.f;
;     if (relc + 63 <= -559) cb = cL;
;     else if (relc - 31 >= 559) cb = cR;
;     else {
; #pragma unroll
;         for (int r = 0; r < 16; ++r) { p0[r] += tbp[(r & 3) + 8 * (r >> 2)]; p1[r] += tbp[32 + (r & 3) + 8 * (r >> 2)]; }
;     }
;     float pmax = p0[0];
; #pragma unroll
;     for (int r = 1; r < 16; ++r) pmax = fmaxf(pmax, p0[r]);
; #pragma unroll
;     for (int r = 0; r < 16; ++r) pmax = fmaxf(pmax, p1[r]);
;     pmax = half_max(pmax) + cb;
;     if (__builtin_expect(__all(pmax - m_reg <= 8.f), 1)) { mn = m_reg; alpha = 1.f; }
;     else { mn = fmaxf(m_reg, pmax); alpha = __builtin_amdgcn_exp2f(m_reg - mn); m_reg = mn; }
;     const float sh = mn - cb;
; #pragma unroll
;     for (int r = 0; r < 16; ++r) { p0[r] -= sh; p1[r] -= sh; }
; #pragma unroll
;     for (int r = 0; r < 16; ++r) p0[r] = __builtin_amdgcn_exp2f(p0[r]);
; }
; __device__ __forceinline__ void unit(LAS unsigned char* lds, const bf16* __restrict__ PROJ, bf16* __restrict__ MIXED, const float* __restrict__ subln_g, float lam, int R0, int seq, int h, int qb) {
;     ...
;     SBAR(); qkt(pB0, pB1, K_lds + SHM_K, qr, r32, cb0);
;     finishSM(pA0, pA1, alA, l_reg, pa0, pa1, pa2, pa3); SBAR();
;     pv_d0(o, vb0, pa0, pa1, pa2, pa3); partialSM(pB0, pB1, tbq + (NT - 1) * 64, rc0 + (NT - 1) * 64, cL, cR, m_reg, mnB, alB);
;     __syncthreads(); RESC(alB);
;     finishSM(pB0, pB1, alB, l_reg, pa0, pa1, pa2, pa3); SBAR();
.Lmb_pv_pe:
	s_nop 5
	s_waitcnt lgkmcnt(0)
	v_mfma_f32_32x32x16_bf16 v[0:15], v[232:235], v[240:243], v[0:15]
	ds_read_b64_tr_b16 v[240:241], v175 offset:512
	ds_read_b64_tr_b16 v[242:243], v175 offset:2560
	v_max3_f32 v254, v80, v81, v82
	v_max3_f32 v255, v83, v84, v85
	v_max3_f32 v254, v254, v86, v87
	v_max3_f32 v255, v255, v88, v89
	v_max3_f32 v254, v254, v90, v91
	v_max3_f32 v255, v255, v92, v93
	v_mfma_f32_32x32x16_bf16 v[0:15], v[236:239], v[244:247], v[0:15]
	ds_read_b64_tr_b16 v[244:245], v175 offset:4608
	ds_read_b64_tr_b16 v[246:247], v175 offset:6656
	v_max3_f32 v254, v254, v94, v95
	v_max3_f32 v255, v255, v64, v65
	v_max3_f32 v254, v254, v66, v67
	v_max3_f32 v255, v255, v68, v69
	v_max3_f32 v254, v254, v70, v71
	v_max3_f32 v255, v255, v72, v73
	v_mfma_f32_32x32x16_bf16 v[0:15], v[144:147], v[152:155], v[0:15]
	ds_read_b64_tr_b16 v[152:153], v175 offset:8704
	ds_read_b64_tr_b16 v[154:155], v175 offset:10752
	v_max3_f32 v254, v254, v74, v75
	v_max3_f32 v255, v255, v76, v77
	v_max3_f32 v254, v254, v78, v79
	v_max_f32_e32 v254, v254, v255
	v_mov_b32_e32 v255, v254
	v_mfma_f32_32x32x16_bf16 v[0:15], v[148:151], v[156:159], v[0:15]
	ds_read_b64_tr_b16 v[156:157], v175 offset:12800
	ds_read_b64_tr_b16 v[158:159], v175 offset:14848
	v_permlane32_swap_b32_e32 v254, v255
	v_max_f32_e32 v254, v254, v255
	v_add_f32_e32 v254, v249, v254
	v_sub_f32_e32 v255, v254, v250
	v_cmp_ge_f32_e32 vcc, s35, v255
	v_max_f32_e32 v255, v250, v254
	s_waitcnt lgkmcnt(0)
	v_mfma_f32_32x32x16_bf16 v[48:63], v[232:235], v[240:243], v[48:63]
	ds_read_b64_tr_b16 v[240:241], v175 offset:1024
	ds_read_b64_tr_b16 v[242:243], v175 offset:3072
	v_sub_f32_e32 v248, v250, v255
	v_exp_f32_e32 v248, v248
	v_sub_f32_e32 v252, v255, v249
	v_sub_f32_e32 v254, v250, v249
	s_cmp_eq_u64 vcc, exec
	s_cselect_b64 s[4:5], -1, 0
	v_cndmask_b32_e64 v251, v248, 1.0, s[4:5]
	v_mfma_f32_32x32x16_bf16 v[48:63], v[236:239], v[244:247], v[48:63]
	ds_read_b64_tr_b16 v[244:245], v175 offset:5120
	ds_read_b64_tr_b16 v[246:247], v175 offset:7168
	v_cndmask_b32_e64 v250, v255, v250, s[4:5]
	v_cndmask_b32_e64 v252, v252, v254, s[4:5]
	v_sub_f32_e32 v80, v80, v252
	v_sub_f32_e32 v81, v81, v252
	v_sub_f32_e32 v82, v82, v252
	v_sub_f32_e32 v83, v83, v252
	v_mfma_f32_32x32x16_bf16 v[48:63], v[144:147], v[152:155], v[48:63]
	ds_read_b64_tr_b16 v[152:153], v175 offset:9216
	ds_read_b64_tr_b16 v[154:155], v175 offset:11264
	v_sub_f32_e32 v84, v84, v252
	v_sub_f32_e32 v85, v85, v252
	v_sub_f32_e32 v86, v86, v252
	v_sub_f32_e32 v87, v87, v252
	v_sub_f32_e32 v88, v88, v252
	v_sub_f32_e32 v89, v89, v252
	v_mfma_f32_32x32x16_bf16 v[48:63], v[148:151], v[156:159], v[48:63]
	ds_read_b64_tr_b16 v[156:157], v175 offset:13312
	ds_read_b64_tr_b16 v[158:159], v175 offset:15360
	v_sub_f32_e32 v90, v90, v252
	v_sub_f32_e32 v91, v91, v252
	v_sub_f32_e32 v92, v92, v252
	v_sub_f32_e32 v93, v93, v252
	v_sub_f32_e32 v94, v94, v252
	v_sub_f32_e32 v95, v95, v252
	s_waitcnt lgkmcnt(0)
	v_mfma_f32_32x32x16_bf16 v[32:47], v[232:235], v[240:243], v[32:47]
	ds_read_b64_tr_b16 v[240:241], v175 offset:1536
	ds_read_b64_tr_b16 v[242:243], v175 offset:3584
	v_exp_f32_e32 v80, v80
	v_sub_f32_e32 v64, v64, v252
	v_exp_f32_e32 v81, v81
	v_sub_f32_e32 v65, v65, v252
	v_mfma_f32_32x32x16_bf16 v[32:47], v[236:239], v[244:247], v[32:47]
	ds_read_b64_tr_b16 v[244:245], v175 offset:5632
	ds_read_b64_tr_b16 v[246:247], v175 offset:7680
	v_exp_f32_e32 v82, v82
	v_sub_f32_e32 v66, v66, v252
	v_exp_f32_e32 v83, v83
	v_sub_f32_e32 v67, v67, v252
	v_mfma_f32_32x32x16_bf16 v[32:47], v[144:147], v[152:155], v[32:47]
	ds_read_b64_tr_b16 v[152:153], v175 offset:9728
	ds_read_b64_tr_b16 v[154:155], v175 offset:11776
	v_exp_f32_e32 v84, v84
	v_sub_f32_e32 v68, v68, v252
	v_exp_f32_e32 v85, v85
	v_sub_f32_e32 v69, v69, v252
	v_mfma_f32_32x32x16_bf16 v[32:47], v[148:151], v[156:159], v[32:47]
	ds_read_b64_tr_b16 v[156:157], v175 offset:13824
	ds_read_b64_tr_b16 v[158:159], v175 offset:15872
	v_exp_f32_e32 v86, v86
	v_sub_f32_e32 v70, v70, v252
	v_exp_f32_e32 v87, v87
	v_sub_f32_e32 v71, v71, v252
	s_waitcnt lgkmcnt(0)
	v_mfma_f32_32x32x16_bf16 v[16:31], v[232:235], v[240:243], v[16:31]
	v_exp_f32_e32 v88, v88
	v_sub_f32_e32 v72, v72, v252
	v_exp_f32_e32 v89, v89
	v_sub_f32_e32 v73, v73, v252
	v_mfma_f32_32x32x16_bf16 v[16:31], v[236:239], v[244:247], v[16:31]
	v_exp_f32_e32 v90, v90
	v_sub_f32_e32 v74, v74, v252
	v_exp_f32_e32 v91, v91
	v_sub_f32_e32 v75, v75, v252
	v_mfma_f32_32x32x16_bf16 v[16:31], v[144:147], v[152:155], v[16:31]
	v_exp_f32_e32 v92, v92
	v_sub_f32_e32 v76, v76, v252
	v_exp_f32_e32 v93, v93
	v_sub_f32_e32 v77, v77, v252
	v_mfma_f32_32x32x16_bf16 v[16:31], v[148:151], v[156:159], v[16:31]
	v_exp_f32_e32 v94, v94
	v_sub_f32_e32 v78, v78, v252
	v_exp_f32_e32 v95, v95
	v_sub_f32_e32 v79, v79, v252
	s_waitcnt lgkmcnt(0)
	s_barrier
	s_and_b64 vcc, exec, s[4:5]
	s_cbranch_vccnz .Lmb_nr_pe
	s_and_saveexec_b64 s[28:29], s[0:1]
	ds_write_b32 v215, v251 offset:128
	s_or_b64 exec, exec, s[28:29]
	s_waitcnt lgkmcnt(0)
	ds_read_b128 v[112:115], v179 offset:224
	ds_read_b128 v[116:119], v179 offset:192
	ds_read_b128 v[120:123], v179 offset:160
	ds_read_b128 v[124:127], v179 offset:128
	s_waitcnt lgkmcnt(0)
	s_nop 3
	v_pk_mul_f32 v[14:15], v[14:15], v[114:115]
	v_pk_mul_f32 v[12:13], v[12:13], v[112:113]
	v_pk_mul_f32 v[10:11], v[10:11], v[118:119]
	v_pk_mul_f32 v[8:9], v[8:9], v[116:117]
	v_pk_mul_f32 v[6:7], v[6:7], v[122:123]
	v_pk_mul_f32 v[4:5], v[4:5], v[120:121]
	v_pk_mul_f32 v[2:3], v[2:3], v[126:127]
	v_pk_mul_f32 v[0:1], v[0:1], v[124:125]
	v_pk_mul_f32 v[62:63], v[62:63], v[114:115]
	v_pk_mul_f32 v[60:61], v[60:61], v[112:113]
	v_pk_mul_f32 v[58:59], v[58:59], v[118:119]
	v_pk_mul_f32 v[56:57], v[56:57], v[116:117]
	v_pk_mul_f32 v[54:55], v[54:55], v[122:123]
	v_pk_mul_f32 v[52:53], v[52:53], v[120:121]
	v_pk_mul_f32 v[50:51], v[50:51], v[126:127]
	v_pk_mul_f32 v[48:49], v[48:49], v[124:125]
	v_pk_mul_f32 v[46:47], v[46:47], v[114:115]
	v_pk_mul_f32 v[44:45], v[44:45], v[112:113]
	v_pk_mul_f32 v[42:43], v[42:43], v[118:119]
	v_pk_mul_f32 v[40:41], v[40:41], v[116:117]
	v_pk_mul_f32 v[38:39], v[38:39], v[122:123]
	v_pk_mul_f32 v[36:37], v[36:37], v[120:121]
	v_pk_mul_f32 v[34:35], v[34:35], v[126:127]
	v_pk_mul_f32 v[32:33], v[32:33], v[124:125]
	v_pk_mul_f32 v[30:31], v[30:31], v[114:115]
	v_pk_mul_f32 v[28:29], v[28:29], v[112:113]
	v_pk_mul_f32 v[26:27], v[26:27], v[118:119]
	v_pk_mul_f32 v[24:25], v[24:25], v[116:117]
	v_pk_mul_f32 v[22:23], v[22:23], v[122:123]
	v_pk_mul_f32 v[20:21], v[20:21], v[120:121]
	v_pk_mul_f32 v[18:19], v[18:19], v[126:127]
	v_pk_mul_f32 v[16:17], v[16:17], v[124:125]
